# P4: per-XCD column-tile rotation + 8-group stagger (1.6us)
# speedup vs baseline: 1.0153x; 1.0021x over previous
;     __host__ __device__ bool next(int i, Unit& u) const {
;     ...
;         int wgid = (int)L; { const int q = nwg / NXCD, r = nwg % NXCD, xcd = wgid % NXCD, off = wgid / NXCD; wgid = (xcd < r ? xcd * (q + 1) : r * (q + 1) + (xcd - r) * q) + off; }
;         const int nig = WGM * nN, gid = wgid / nig, fm = gid * WGM, gsz = (nM - fm) < WGM ? (nM - fm) : WGM;
;         u.pm = fm + ((wgid % nig) % gsz); u.pn = (wgid % nig) / gsz; u.idx = i; return true;
.Lstg_p4_done:
	s_cbranch_vccnz .LBB0_1370
	s_lshr_b32 s0, s3, 29
	s_add_i32 s0, s2, s0
	s_ashr_i32 s1, s0, 3
	s_and_b32 s0, s0, -8
	s_sub_i32 s0, s2, s0
	s_cmp_lt_i32 s0, 0
	s_movk_i32 s6, 0x181
	s_cselect_b32 s6, s6, 0x180
	s_mul_i32 s0, s0, s6
	s_add_i32 s0, s0, s1
	s_ashr_i32 s1, s0, 31
	s_lshr_b32 s1, s1, 25
	s_add_i32 s1, s0, s1
	s_ashr_i32 s6, s1, 7
	s_and_b32 s1, s1, 0xff80
	s_sub_i32 s0, s0, s1
	s_bfe_i32 s1, s0, 0x80000
	s_bfe_u32 s1, s1, 0x3000c
	s_add_i32 s1, s0, s1
	s_and_b32 s7, s1, 0xf8
	s_sub_i32 s0, s0, s7
	s_lshl_b32 s6, s6, 3
	s_sext_i32_i8 s0, s0
	s_add_i32 s24, s6, s0
	s_bfe_i32 s0, s1, 0x80000
	s_sext_i32_i16 s0, s0
	s_ashr_i32 s22, s0, 3
	s_and_b32 s98, s2, 7
	s_lshl_b32 s98, s98, 2
	s_add_i32 s22, s22, s98
	s_and_b32 s22, s22, 15
	s_and_b64 vcc, exec, s[4:5]
	s_cbranch_vccz .LBB0_1371

;     __host__ __device__ bool next(int i, Unit& u) const {
;         if (i >= R) return false;
;         const long L = (long)(rev ? R - 1 - i : i) * G + c; if (L >= nwg) return false;
;         int wgid = (int)L; { const int q = nwg / NXCD, r = nwg % NXCD, xcd = wgid % NXCD, off = wgid / NXCD; wgid = (xcd < r ? xcd * (q + 1) : r * (q + 1) + (xcd - r) * q) + off; }
;         const int nig = WGM * nN, gid = wgid / nig, fm = gid * WGM, gsz = (nM - fm) < WGM ? (nM - fm) : WGM;
;         u.pm = fm + ((wgid % nig) % gsz); u.pn = (wgid % nig) / gsz; u.idx = i; return true;
; template <class Epi, class Sched, bool ALIGN_EPI = false, bool SP2 = false>
; __device__ __forceinline__ void gemm_phase(PG8_LAS unsigned char* lds, const Gemm g, const Sched& S, const Epi& E) {
;     ...
;         const bool has_next = S.next(ui + 1, nxt);
.LBB0_1376:
	s_add_i32 s47, s47, 1
	s_cmp_ge_i32 s47, s30
	s_mov_b64 s[16:17], 0
	s_cbranch_scc1 .LBB0_1379
	s_mul_i32 s0, s47, s43
	s_mul_hi_u32 s1, s47, s42
	s_add_i32 s1, s1, s0
	s_mul_i32 s0, s47, s42
	s_add_u32 s18, s0, s2
	s_addc_u32 s19, s1, s3
	v_cmp_gt_i64_e32 vcc, s[18:19], v[144:145]
	s_cbranch_vccnz .LBB0_1379
	s_ashr_i32 s0, s18, 31
	s_lshr_b32 s0, s0, 29
	s_add_i32 s0, s18, s0
	s_ashr_i32 s1, s0, 3
	s_and_b32 s0, s0, -8
	s_sub_i32 s0, s18, s0
	s_cmp_lt_i32 s0, 0
	s_cselect_b32 s8, s40, 0x180
	s_mul_i32 s0, s0, s8
	s_add_i32 s0, s0, s1
	s_ashr_i32 s1, s0, 31
	s_lshr_b32 s1, s1, 25
	s_add_i32 s1, s0, s1
	s_ashr_i32 s8, s1, 7
	s_lshl_b32 s9, s8, 3
	s_sub_i32 s8, 0xc0, s9
	s_min_i32 s14, s8, 8
	s_abs_i32 s8, s14
	v_cvt_f32_u32_e32 v2, s8
	s_sub_i32 s16, 0, s8
	s_and_b32 s1, s1, 0xffffff80
	s_sub_i32 s0, s0, s1
	v_rcp_iflag_f32_e32 v2, v2
	s_abs_i32 s1, s0
	s_xor_b32 s15, s0, s14
	s_ashr_i32 s15, s15, 31
	v_mul_f32_e32 v2, 0x4f7ffffe, v2
	v_cvt_u32_f32_e32 v2, v2
	s_mov_b32 s48, s47
	v_readfirstlane_b32 s17, v2
	s_mul_i32 s16, s16, s17
	s_mul_hi_u32 s16, s17, s16
	s_add_i32 s17, s17, s16
	s_mul_hi_u32 s16, s1, s17
	s_mul_i32 s17, s16, s8
	s_sub_i32 s1, s1, s17
	s_add_i32 s18, s16, 1
	s_sub_i32 s17, s1, s8
	s_cmp_ge_u32 s1, s8
	s_cselect_b32 s16, s18, s16
	s_cselect_b32 s1, s17, s1
	s_add_i32 s17, s16, 1
	s_cmp_ge_u32 s1, s8
	s_cselect_b32 s1, s17, s16
	s_xor_b32 s1, s1, s15
	s_sub_i32 s8, s1, s15
	s_mul_i32 s1, s8, s14
	s_sub_i32 s0, s0, s1
	s_add_i32 s14, s9, s0
	s_and_b32 s98, s2, 7
	s_lshl_b32 s98, s98, 2
	s_add_i32 s8, s8, s98
	s_and_b32 s8, s8, 15
	s_mov_b64 s[16:17], -1
